# stack4: stack3 + up-GEMM epilogue re-emitted so each half's row stores issue mid-block (overlap with the conv/gate arithmetic)
# speedup vs baseline: 1.0148x; 1.0104x over previous
.LBB0_738:
	s_or_b64 exec, exec, s[0:1]
	s_mov_b32 s0, 0
	v_pk_fma_f32 v[46:47], v[142:143], v[186:187], v[146:147]
	v_mov_b32_dpp v48, v186 row_shr:1 row_mask:0xf bank_mask:0xf bound_ctrl:1
	v_mov_b32_dpp v49, v187 row_shr:1 row_mask:0xf bank_mask:0xf bound_ctrl:1
	v_mov_b32_dpp v186, v182 row_shr:1 row_mask:0xf bank_mask:0xf bound_ctrl:1
	v_pk_fma_f32 v[46:47], v[126:127], v[170:171], v[46:47]
	v_mov_b32_dpp v187, v183 row_shr:1 row_mask:0xf bank_mask:0xf bound_ctrl:1
	v_pk_fma_f32 v[182:183], v[182:183], v[162:163], v[166:167]
	v_pk_fma_f32 v[46:47], v[122:123], v[158:159], v[46:47]
	v_mov_b32_dpp v198, v170 row_shr:1 row_mask:0xf bank_mask:0xf bound_ctrl:1
	v_pk_fma_f32 v[182:183], v[114:115], v[178:179], v[182:183]
	v_pk_mul_f32 v[200:201], v[46:47], s[82:83] op_sel_hi:[1,0]
	v_mov_b32_dpp v199, v171 row_shr:1 row_mask:0xf bank_mask:0xf bound_ctrl:1
	v_pk_fma_f32 v[182:183], v[110:111], v[194:195], v[182:183]
	v_exp_f32_e32 v202, v200
	v_exp_f32_e32 v203, v201
	v_pk_fma_f32 v[200:201], v[184:185], v[164:165], v[168:169]
	v_mov_b32_dpp v204, v178 row_shr:1 row_mask:0xf bank_mask:0xf bound_ctrl:1
	v_pk_fma_f32 v[170:171], v[170:171], v[142:143], v[146:147]
	v_pk_add_f32 v[202:203], v[202:203], 1.0 op_sel_hi:[1,0]
	v_pk_fma_f32 v[200:201], v[116:117], v[180:181], v[200:201]
	v_mov_b32_dpp v205, v179 row_shr:1 row_mask:0xf bank_mask:0xf bound_ctrl:1
	v_rcp_f32_e32 v206, v202
	v_rcp_f32_e32 v207, v203
	v_pk_fma_f32 v[170:171], v[126:127], v[158:159], v[170:171]
	v_pk_fma_f32 v[200:201], v[112:113], v[196:197], v[200:201]
	v_pk_fma_f32 v[202:203], v[180:181], v[164:165], v[168:169]
	v_pk_mul_f32 v[46:47], v[46:47], v[206:207]
	v_pk_fma_f32 v[170:171], v[122:123], v[154:155], v[170:171]
	v_pk_fma_f32 v[178:179], v[178:179], v[162:163], v[166:167]
	v_pk_mul_f32 v[46:47], v[182:183], v[46:47]
	v_pk_mul_f32 v[182:183], v[170:171], s[82:83] op_sel_hi:[1,0]
	v_pk_fma_f32 v[202:203], v[196:197], v[116:117], v[202:203]
	v_pk_fma_f32 v[178:179], v[194:195], v[114:115], v[178:179]
	v_exp_f32_e32 v206, v182
	v_exp_f32_e32 v207, v183
	v_pk_fma_f32 v[182:183], v[112:113], v[192:193], v[202:203]
	v_pk_fma_f32 v[178:179], v[110:111], v[190:191], v[178:179]
	v_pk_fma_f32 v[196:197], v[196:197], v[164:165], v[168:169]
	v_pk_add_f32 v[202:203], v[206:207], 1.0 op_sel_hi:[1,0]
	v_pk_fma_f32 v[158:159], v[158:159], v[142:143], v[146:147]
	v_pk_fma_f32 v[194:195], v[194:195], v[162:163], v[166:167]
	v_rcp_f32_e32 v206, v202
	v_rcp_f32_e32 v207, v203
	v_pk_fma_f32 v[158:159], v[154:155], v[126:127], v[158:159]
	v_pk_fma_f32 v[154:155], v[154:155], v[142:143], v[146:147]
	v_pk_fma_f32 v[196:197], v[192:193], v[116:117], v[196:197]
	v_pk_mul_f32 v[170:171], v[170:171], v[206:207]
	v_pk_fma_f32 v[158:159], v[122:123], v[48:49], v[158:159]
	v_pk_fma_f32 v[48:49], v[126:127], v[48:49], v[154:155]
	v_pk_mul_f32 v[154:155], v[178:179], v[170:171]
	v_pk_fma_f32 v[170:171], v[190:191], v[114:115], v[194:195]
	v_pk_fma_f32 v[48:49], v[122:123], v[198:199], v[48:49]
	v_pk_fma_f32 v[178:179], v[190:191], v[162:163], v[166:167]
	v_pk_mul_f32 v[190:191], v[158:159], s[82:83] op_sel_hi:[1,0]
	v_pk_mul_f32 v[194:195], v[48:49], s[82:83] op_sel_hi:[1,0]
	v_pk_fma_f32 v[178:179], v[114:115], v[186:187], v[178:179]
	v_exp_f32_e32 v198, v190
	v_exp_f32_e32 v202, v194
	v_exp_f32_e32 v203, v195
	v_pk_fma_f32 v[178:179], v[110:111], v[204:205], v[178:179]
	v_exp_f32_e32 v199, v191
	v_pk_fma_f32 v[170:171], v[110:111], v[186:187], v[170:171]
	v_pk_add_f32 v[186:187], v[202:203], 1.0 op_sel_hi:[1,0]
	v_pk_add_f32 v[190:191], v[198:199], 1.0 op_sel_hi:[1,0]
	v_rcp_f32_e32 v194, v186
	v_rcp_f32_e32 v195, v187
	v_rcp_f32_e32 v186, v190
	v_rcp_f32_e32 v187, v191
	v_pk_mul_f32 v[48:49], v[48:49], v[194:195]
	v_pk_mul_f32 v[158:159], v[158:159], v[186:187]
	v_pk_mul_f32 v[48:49], v[178:179], v[48:49]
	v_pk_fma_f32 v[178:179], v[192:193], v[164:165], v[168:169]
	v_pk_mul_f32 v[158:159], v[170:171], v[158:159]
	v_mov_b32_dpp v170, v184 row_shr:1 row_mask:0xf bank_mask:0xf bound_ctrl:1
	v_mov_b32_dpp v186, v188 row_shr:1 row_mask:0xf bank_mask:0xf bound_ctrl:1
	v_pk_fma_f32 v[190:191], v[172:173], v[144:145], v[148:149]
	v_mov_b32_dpp v187, v189 row_shr:1 row_mask:0xf bank_mask:0xf bound_ctrl:1
	v_mov_b32_dpp v192, v172 row_shr:1 row_mask:0xf bank_mask:0xf bound_ctrl:1
	v_pk_fma_f32 v[194:195], v[144:145], v[188:189], v[148:149]
	v_pk_fma_f32 v[190:191], v[128:129], v[160:161], v[190:191]
	v_mov_b32_dpp v193, v173 row_shr:1 row_mask:0xf bank_mask:0xf bound_ctrl:1
	v_pk_fma_f32 v[194:195], v[128:129], v[172:173], v[194:195]
	v_pk_fma_f32 v[190:191], v[124:125], v[156:157], v[190:191]
	v_mov_b32_dpp v171, v185 row_shr:1 row_mask:0xf bank_mask:0xf bound_ctrl:1
	v_pk_fma_f32 v[194:195], v[124:125], v[160:161], v[194:195]
	v_pk_mul_f32 v[198:199], v[190:191], s[82:83] op_sel_hi:[1,0]
	v_mov_b32_dpp v202, v180 row_shr:1 row_mask:0xf bank_mask:0xf bound_ctrl:1
	v_pk_mul_f32 v[204:205], v[194:195], s[82:83] op_sel_hi:[1,0]
	v_exp_f32_e32 v206, v198
	v_exp_f32_e32 v207, v199
	v_exp_f32_e32 v198, v204
	v_exp_f32_e32 v199, v205
	v_mov_b32_dpp v203, v181 row_shr:1 row_mask:0xf bank_mask:0xf bound_ctrl:1
	v_pk_fma_f32 v[196:197], v[112:113], v[170:171], v[196:197]
	v_pk_fma_f32 v[170:171], v[116:117], v[170:171], v[178:179]
	v_pk_add_f32 v[178:179], v[198:199], 1.0 op_sel_hi:[1,0]
	v_pk_add_f32 v[198:199], v[206:207], 1.0 op_sel_hi:[1,0]
	v_pk_fma_f32 v[170:171], v[112:113], v[202:203], v[170:171]
	v_rcp_f32_e32 v202, v178
	v_rcp_f32_e32 v203, v179
	v_rcp_f32_e32 v178, v198
	v_rcp_f32_e32 v179, v199
	v_pk_fma_f32 v[198:199], v[160:161], v[144:145], v[148:149]
	v_pk_mul_f32 v[194:195], v[194:195], v[202:203]
	v_pk_fma_f32 v[202:203], v[156:157], v[144:145], v[148:149]
	v_pk_mul_f32 v[178:179], v[190:191], v[178:179]
	v_pk_fma_f32 v[190:191], v[156:157], v[128:129], v[198:199]
	v_pk_fma_f32 v[198:199], v[128:129], v[186:187], v[202:203]
	v_mov_b32_dpp v202, v102 row_shr:1 row_mask:0xf bank_mask:0xf bound_ctrl:1
	v_pk_fma_f32 v[186:187], v[124:125], v[186:187], v[190:191]
	v_pk_fma_f32 v[190:191], v[124:125], v[192:193], v[198:199]
	v_pk_mul_f32 v[192:193], v[186:187], s[82:83] op_sel_hi:[1,0]
	v_pk_mul_f32 v[198:199], v[190:191], s[82:83] op_sel_hi:[1,0]
	v_exp_f32_e32 v204, v192
	v_exp_f32_e32 v205, v193
	v_exp_f32_e32 v192, v198
	v_exp_f32_e32 v193, v199
	v_mov_b32_dpp v203, v103 row_shr:1 row_mask:0xf bank_mask:0xf bound_ctrl:1
	v_pk_add_f32 v[198:199], v[204:205], 1.0 op_sel_hi:[1,0]
	v_pk_fma_f32 v[102:103], v[102:103], v[26:27], v[30:31]
	v_pk_add_f32 v[192:193], v[192:193], 1.0 op_sel_hi:[1,0]
	v_rcp_f32_e32 v204, v198
	v_rcp_f32_e32 v205, v199
	v_rcp_f32_e32 v198, v192
	v_rcp_f32_e32 v199, v193
	v_pk_fma_f32 v[102:103], v[78:79], v[6:7], v[102:103]
	v_pk_mul_f32 v[186:187], v[186:187], v[204:205]
	v_mov_b32_dpp v192, v78 row_shr:1 row_mask:0xf bank_mask:0xf bound_ctrl:1
	v_pk_mul_f32 v[190:191], v[190:191], v[198:199]
	v_pk_fma_f32 v[102:103], v[150:151], v[2:3], v[102:103]
	v_mov_b32_dpp v193, v79 row_shr:1 row_mask:0xf bank_mask:0xf bound_ctrl:1
	v_pk_mul_f32 v[170:171], v[170:171], v[190:191]
	v_pk_fma_f32 v[78:79], v[78:79], v[26:27], v[30:31]
	v_pk_fma_f32 v[190:191], v[104:105], v[28:29], v[32:33]
	v_mov_b32_dpp v198, v82 row_shr:1 row_mask:0xf bank_mask:0xf bound_ctrl:1
	v_pk_fma_f32 v[78:79], v[150:151], v[6:7], v[78:79]
	v_mov_b32_dpp v204, v106 row_shr:1 row_mask:0xf bank_mask:0xf bound_ctrl:1
	v_mov_b32_dpp v205, v107 row_shr:1 row_mask:0xf bank_mask:0xf bound_ctrl:1
	v_pk_fma_f32 v[106:107], v[106:107], v[18:19], v[22:23]
	v_pk_fma_f32 v[78:79], v[138:139], v[2:3], v[78:79]
	v_mov_b32_dpp v199, v83 row_shr:1 row_mask:0xf bank_mask:0xf bound_ctrl:1
	v_pk_fma_f32 v[106:107], v[82:83], v[14:15], v[106:107]
	v_pk_fma_f32 v[82:83], v[82:83], v[18:19], v[22:23]
	v_pk_fma_f32 v[206:207], v[66:67], v[18:19], v[22:23]
	v_pk_fma_f32 v[106:107], v[66:67], v[10:11], v[106:107]
	v_pk_fma_f32 v[66:67], v[66:67], v[14:15], v[82:83]
	v_pk_fma_f32 v[82:83], v[80:81], v[8:9], v[190:191]
	v_pk_mul_f32 v[190:191], v[106:107], s[82:83] op_sel_hi:[1,0]
	v_pk_fma_f32 v[66:67], v[54:55], v[10:11], v[66:67]
	v_pk_fma_f32 v[206:207], v[54:55], v[14:15], v[206:207]
	v_pk_fma_f32 v[54:55], v[54:55], v[18:19], v[22:23]
	v_pk_fma_f32 v[82:83], v[152:153], v[4:5], v[82:83]
	v_pk_fma_f32 v[206:207], v[10:11], v[204:205], v[206:207]
	v_pk_fma_f32 v[54:55], v[14:15], v[204:205], v[54:55]
	v_exp_f32_e32 v204, v190
	v_exp_f32_e32 v205, v191
	v_pk_fma_f32 v[190:191], v[80:81], v[28:29], v[32:33]
	v_pk_mul_f32 v[194:195], v[200:201], v[194:195]
	v_pk_mul_f32 v[200:201], v[66:67], s[82:83] op_sel_hi:[1,0]
	v_pk_add_f32 v[204:205], v[204:205], 1.0 op_sel_hi:[1,0]
	v_pk_fma_f32 v[190:191], v[152:153], v[8:9], v[190:191]
	v_pk_mul_f32 v[178:179], v[182:183], v[178:179]
	v_rcp_f32_e32 v182, v204
	v_rcp_f32_e32 v183, v205
	v_exp_f32_e32 v204, v200
	v_exp_f32_e32 v205, v201
	v_pk_fma_f32 v[190:191], v[140:141], v[4:5], v[190:191]
	v_pk_mul_f32 v[106:107], v[106:107], v[182:183]
	v_pk_fma_f32 v[182:183], v[152:153], v[28:29], v[32:33]
	v_pk_add_f32 v[200:201], v[204:205], 1.0 op_sel_hi:[1,0]
	v_pk_mul_f32 v[102:103], v[102:103], v[106:107]
	v_pk_fma_f32 v[106:107], v[150:151], v[26:27], v[30:31]
	v_rcp_f32_e32 v204, v200
	v_rcp_f32_e32 v205, v201
	v_pk_mul_f32 v[200:201], v[206:207], s[82:83] op_sel_hi:[1,0]
	v_pk_fma_f32 v[106:107], v[138:139], v[6:7], v[106:107]
	v_pk_fma_f32 v[182:183], v[140:141], v[8:9], v[182:183]
	v_pk_mul_f32 v[66:67], v[66:67], v[204:205]
	v_exp_f32_e32 v204, v200
	v_exp_f32_e32 v205, v201
	v_pk_mul_f32 v[66:67], v[78:79], v[66:67]
	v_pk_fma_f32 v[78:79], v[2:3], v[202:203], v[106:107]
	v_pk_mul_f32 v[106:107], v[196:197], v[186:187]
	v_pk_add_f32 v[186:187], v[204:205], 1.0 op_sel_hi:[1,0]
	v_mov_b32_e32 v0, v158
	v_pk_fma_f32 v[54:55], v[10:11], v[198:199], v[54:55]
	v_rcp_f32_e32 v196, v186
	v_rcp_f32_e32 v197, v187
	v_pk_mul_f32 v[186:187], v[54:55], s[82:83] op_sel_hi:[1,0]
	v_pk_fma_f32 v[198:199], v[138:139], v[26:27], v[30:31]
	v_pk_mul_f32 v[196:197], v[206:207], v[196:197]
	v_exp_f32_e32 v200, v186
	v_exp_f32_e32 v201, v187
	v_pk_mul_f32 v[78:79], v[78:79], v[196:197]
	v_pk_fma_f32 v[186:187], v[6:7], v[202:203], v[198:199]
	v_pk_add_f32 v[196:197], v[200:201], 1.0 op_sel_hi:[1,0]
	v_pk_fma_f32 v[186:187], v[2:3], v[192:193], v[186:187]
	v_pk_fma_f32 v[192:193], v[84:85], v[20:21], v[24:25]
	v_rcp_f32_e32 v198, v196
	v_rcp_f32_e32 v199, v197
	v_pk_fma_f32 v[192:193], v[68:69], v[16:17], v[192:193]
	v_pk_mul_f32 v[54:55], v[54:55], v[198:199]
	v_pk_fma_f32 v[192:193], v[56:57], v[12:13], v[192:193]
	v_pk_mul_f32 v[54:55], v[186:187], v[54:55]
	v_pk_fma_f32 v[186:187], v[140:141], v[28:29], v[32:33]
	v_mov_b32_dpp v196, v84 row_shr:1 row_mask:0xf bank_mask:0xf bound_ctrl:1
	v_mov_b32_dpp v197, v85 row_shr:1 row_mask:0xf bank_mask:0xf bound_ctrl:1
	v_mov_b32_dpp v198, v80 row_shr:1 row_mask:0xf bank_mask:0xf bound_ctrl:1
	v_mov_b32_dpp v199, v81 row_shr:1 row_mask:0xf bank_mask:0xf bound_ctrl:1
	v_pk_mul_f32 v[200:201], v[192:193], s[82:83] op_sel_hi:[1,0]
	v_mov_b32_dpp v202, v104 row_shr:1 row_mask:0xf bank_mask:0xf bound_ctrl:1
	v_mov_b32_dpp v203, v105 row_shr:1 row_mask:0xf bank_mask:0xf bound_ctrl:1
	v_mov_b32_dpp v204, v108 row_shr:1 row_mask:0xf bank_mask:0xf bound_ctrl:1
	v_exp_f32_e32 v206, v200
	v_exp_f32_e32 v207, v201
	v_pk_fma_f32 v[200:201], v[108:109], v[20:21], v[24:25]
	v_mov_b32_dpp v205, v109 row_shr:1 row_mask:0xf bank_mask:0xf bound_ctrl:1
	v_pk_fma_f32 v[182:183], v[4:5], v[202:203], v[182:183]
	v_pk_fma_f32 v[200:201], v[84:85], v[16:17], v[200:201]
	v_pk_fma_f32 v[186:187], v[8:9], v[202:203], v[186:187]
	v_pk_add_f32 v[202:203], v[206:207], 1.0 op_sel_hi:[1,0]
	v_pk_fma_f32 v[200:201], v[68:69], v[12:13], v[200:201]
	v_pk_fma_f32 v[186:187], v[4:5], v[198:199], v[186:187]
	v_rcp_f32_e32 v198, v202
	v_pk_mul_f32 v[206:207], v[200:201], s[82:83] op_sel_hi:[1,0]
	v_rcp_f32_e32 v199, v203
	v_pk_fma_f32 v[202:203], v[68:69], v[20:21], v[24:25]
	v_pk_mul_f32 v[192:193], v[192:193], v[198:199]
	v_exp_f32_e32 v198, v206
	v_exp_f32_e32 v199, v207
	v_pk_mul_f32 v[190:191], v[190:191], v[192:193]
	v_pk_fma_f32 v[192:193], v[56:57], v[16:17], v[202:203]
	v_pk_fma_f32 v[56:57], v[56:57], v[20:21], v[24:25]
	v_pk_add_f32 v[198:199], v[198:199], 1.0 op_sel_hi:[1,0]
	v_pk_fma_f32 v[192:193], v[12:13], v[204:205], v[192:193]
	v_pk_fma_f32 v[56:57], v[16:17], v[204:205], v[56:57]
	v_rcp_f32_e32 v202, v198
	v_rcp_f32_e32 v203, v199
	v_pk_mul_f32 v[198:199], v[192:193], s[82:83] op_sel_hi:[1,0]
	v_pk_fma_f32 v[56:57], v[12:13], v[196:197], v[56:57]
	v_mov_b32_e32 v158, v194
	v_pk_mul_f32 v[196:197], v[200:201], v[202:203]
	v_exp_f32_e32 v200, v198
	v_exp_f32_e32 v201, v199
	v_pk_mul_f32 v[198:199], v[56:57], s[82:83] op_sel_hi:[1,0]
	v_mov_b32_e32 v178, v178
	v_mov_b32_e32 v107, v107
	v_mov_b32_e32 v170, v170
	v_exp_f32_e32 v202, v198
	v_pk_add_f32 v[200:201], v[200:201], 1.0 op_sel_hi:[1,0]
	v_exp_f32_e32 v203, v199
	v_rcp_f32_e32 v198, v200
	v_rcp_f32_e32 v199, v201
	v_pk_add_f32 v[200:201], v[202:203], 1.0 op_sel_hi:[1,0]
	v_mov_b32_e32 v78, v78
	v_mov_b32_e32 v55, v55
	v_pk_mul_f32 v[192:193], v[192:193], v[198:199]
	v_rcp_f32_e32 v198, v200
	v_rcp_f32_e32 v199, v201
	v_pk_mul_f32 v[82:83], v[82:83], v[196:197]
	v_mov_b32_e32 v190, v190
	v_pk_mul_f32 v[56:57], v[56:57], v[198:199]
	v_pk_mul_f32 v[56:57], v[186:187], v[56:57]
	v_pk_mul_f32 v[182:183], v[182:183], v[192:193]
	v_mbcnt_lo_u32_b32 v194, -1, s0
	v_mov_b64_e32 v[186:187], s[12:13]
	v_cvt_pk_bf16_f32 v196, v48, v49
	v_mbcnt_hi_u32_b32 v194, -1, v194
	v_cvt_pk_bf16_f32 v197, v170, v171
	v_cvt_pk_bf16_f32 v198, v54, v55
	v_and_b32_e32 v48, 15, v194
	v_ashrrev_i32_e32 v49, 1, v194
	v_cvt_pk_bf16_f32 v199, v56, v57
	v_cmp_ne_u32_e64 s[98:99], 0, v48
	s_nop 3
	v_and_b32_e32 v49, -8, v49
	v_lshl_or_b32 v48, v48, 2, s21
	v_cvt_pk_bf16_f32 v200, v0, v159
	v_add_u32_e32 v54, s19, v49
	v_or_b32_e32 v0, 1, v48
	v_mad_i64_i32 v[56:57], s[2:3], v48, s94, v[186:187]
	v_ashrrev_i32_e32 v55, 31, v54
	v_mad_i64_i32 v[170:171], s[2:3], v0, s94, v[186:187]
	v_cvt_pk_bf16_f32 v201, v106, v107
	v_lshlrev_b64 v[54:55], 1, v[54:55]
	v_cvt_pk_bf16_f32 v202, v78, v79
	v_cvt_pk_bf16_f32 v203, v182, v183
	v_lshl_add_u64 v[56:57], v[56:57], 0, v[54:55]
	v_lshl_add_u64 v[78:79], v[170:171], 0, v[54:55]
	v_or_b32_e32 v0, 2, v48
	s_mov_b64 exec, s[98:99]
	global_store_dwordx4 v[56:57], v[196:199], off
	s_mov_b64 exec, -1
	s_mov_b64 exec, s[98:99]
	global_store_dwordx4 v[78:79], v[200:203], off
	s_mov_b64 exec, -1
	v_mov_b64_e32 v[106:107], s[12:13]
	v_cvt_pk_bf16_f32 v204, v154, v155
	v_cvt_pk_bf16_f32 v205, v178, v179
	v_mad_i64_i32 v[56:57], s[0:1], v0, s94, v[106:107]
	v_cvt_pk_bf16_f32 v206, v66, v67
	v_cvt_pk_bf16_f32 v207, v190, v191
	v_lshl_add_u64 v[56:57], v[56:57], 0, v[54:55]
	v_or_b32_e32 v0, 3, v48
	v_cvt_pk_bf16_f32 v199, v82, v83
	global_store_dwordx4 v[56:57], v[204:207], off
	v_mad_i64_i32 v[66:67], s[0:1], v0, s94, v[106:107]
	v_cvt_pk_bf16_f32 v196, v46, v47
	v_cvt_pk_bf16_f32 v197, v158, v195
	v_cvt_pk_bf16_f32 v198, v102, v103
	v_lshl_add_u64 v[46:47], v[66:67], 0, v[54:55]
	global_store_dwordx4 v[46:47], v[196:199], off
	v_mov_b32_dpp v56, v98 row_shr:1 row_mask:0xf bank_mask:0xf bound_ctrl:1
	v_mov_b32_dpp v57, v99 row_shr:1 row_mask:0xf bank_mask:0xf bound_ctrl:1
	v_pk_fma_f32 v[66:67], v[142:143], v[98:99], v[146:147]
	v_pk_fma_f32 v[46:47], v[144:145], v[100:101], v[148:149]
	v_mov_b32_dpp v78, v90 row_shr:1 row_mask:0xf bank_mask:0xf bound_ctrl:1
	v_pk_fma_f32 v[66:67], v[126:127], v[94:95], v[66:67]
	v_pk_fma_f32 v[46:47], v[128:129], v[96:97], v[46:47]
	v_mov_b32_dpp v79, v91 row_shr:1 row_mask:0xf bank_mask:0xf bound_ctrl:1
	v_pk_fma_f32 v[66:67], v[122:123], v[118:119], v[66:67]
	v_pk_fma_f32 v[46:47], v[124:125], v[120:121], v[46:47]
	v_pk_fma_f32 v[82:83], v[162:163], v[90:91], v[166:167]
	v_pk_mul_f32 v[90:91], v[66:67], s[82:83] op_sel_hi:[1,0]
	v_mov_b32_dpp v98, v94 row_shr:1 row_mask:0xf bank_mask:0xf bound_ctrl:1
	v_pk_fma_f32 v[82:83], v[114:115], v[86:87], v[82:83]
	v_exp_f32_e32 v102, v90
	v_exp_f32_e32 v103, v91
	v_pk_fma_f32 v[82:83], v[110:111], v[174:175], v[82:83]
	v_mov_b32_dpp v99, v95 row_shr:1 row_mask:0xf bank_mask:0xf bound_ctrl:1
	v_pk_fma_f32 v[90:91], v[144:145], v[96:97], v[148:149]
	v_pk_add_f32 v[102:103], v[102:103], 1.0 op_sel_hi:[1,0]
	v_pk_fma_f32 v[94:95], v[142:143], v[94:95], v[146:147]
	v_pk_fma_f32 v[90:91], v[128:129], v[120:121], v[90:91]
	v_rcp_f32_e32 v106, v102
	v_rcp_f32_e32 v107, v103
	v_pk_fma_f32 v[94:95], v[126:127], v[118:119], v[94:95]
	v_pk_fma_f32 v[90:91], v[124:125], v[136:137], v[90:91]
	v_pk_fma_f32 v[102:103], v[164:165], v[88:89], v[168:169]
	v_pk_mul_f32 v[66:67], v[66:67], v[106:107]
	v_pk_fma_f32 v[94:95], v[122:123], v[134:135], v[94:95]
	v_pk_fma_f32 v[102:103], v[116:117], v[176:177], v[102:103]
	v_pk_mul_f32 v[66:67], v[82:83], v[66:67]
	v_pk_mul_f32 v[82:83], v[94:95], s[82:83] op_sel_hi:[1,0]
	v_pk_fma_f32 v[102:103], v[112:113], v[132:133], v[102:103]
	v_mov_b32_dpp v106, v86 row_shr:1 row_mask:0xf bank_mask:0xf bound_ctrl:1
	v_exp_f32_e32 v154, v82
	v_exp_f32_e32 v155, v83
	v_mov_b32_dpp v107, v87 row_shr:1 row_mask:0xf bank_mask:0xf bound_ctrl:1
	v_pk_fma_f32 v[82:83], v[162:163], v[86:87], v[166:167]
	v_pk_fma_f32 v[86:87], v[142:143], v[118:119], v[146:147]
	v_pk_add_f32 v[118:119], v[154:155], 1.0 op_sel_hi:[1,0]
	v_pk_fma_f32 v[82:83], v[114:115], v[174:175], v[82:83]
	v_pk_fma_f32 v[86:87], v[126:127], v[134:135], v[86:87]
	v_rcp_f32_e32 v154, v118
	v_rcp_f32_e32 v155, v119
	v_pk_fma_f32 v[82:83], v[110:111], v[130:131], v[82:83]
	v_pk_fma_f32 v[118:119], v[144:145], v[120:121], v[148:149]
	v_pk_fma_f32 v[86:87], v[122:123], v[56:57], v[86:87]
	v_pk_mul_f32 v[94:95], v[94:95], v[154:155]
	v_pk_fma_f32 v[118:119], v[128:129], v[136:137], v[118:119]
	v_pk_mul_f32 v[120:121], v[86:87], s[82:83] op_sel_hi:[1,0]
	v_pk_mul_f32 v[82:83], v[82:83], v[94:95]
	v_pk_fma_f32 v[94:95], v[164:165], v[176:177], v[168:169]
	v_exp_f32_e32 v154, v120
	v_exp_f32_e32 v155, v121
	v_pk_fma_f32 v[120:121], v[162:163], v[174:175], v[166:167]
	v_pk_fma_f32 v[94:95], v[116:117], v[132:133], v[94:95]
	v_pk_fma_f32 v[158:159], v[162:163], v[130:131], v[166:167]
	v_pk_fma_f32 v[120:121], v[114:115], v[130:131], v[120:121]
	v_pk_add_f32 v[130:131], v[154:155], 1.0 op_sel_hi:[1,0]
	v_pk_fma_f32 v[114:115], v[114:115], v[78:79], v[158:159]
	v_pk_fma_f32 v[78:79], v[110:111], v[78:79], v[120:121]
	v_rcp_f32_e32 v120, v130
	v_rcp_f32_e32 v121, v131
	v_pk_fma_f32 v[106:107], v[110:111], v[106:107], v[114:115]
	v_pk_fma_f32 v[110:111], v[142:143], v[134:135], v[146:147]
	v_pk_fma_f32 v[114:115], v[164:165], v[132:133], v[168:169]
	v_pk_mul_f32 v[86:87], v[86:87], v[120:121]
	v_pk_fma_f32 v[56:57], v[126:127], v[56:57], v[110:111]
	v_pk_fma_f32 v[110:111], v[144:145], v[136:137], v[148:149]
	v_pk_mul_f32 v[78:79], v[78:79], v[86:87]
	v_pk_fma_f32 v[56:57], v[122:123], v[98:99], v[56:57]
	v_pk_mul_f32 v[86:87], v[56:57], s[82:83] op_sel_hi:[1,0]
	v_pk_fma_f32 v[98:99], v[164:165], v[92:93], v[168:169]
	v_mov_b32_dpp v120, v100 row_shr:1 row_mask:0xf bank_mask:0xf bound_ctrl:1
	v_exp_f32_e32 v122, v86
	v_exp_f32_e32 v123, v87
	v_mov_b32_dpp v121, v101 row_shr:1 row_mask:0xf bank_mask:0xf bound_ctrl:1
	v_pk_fma_f32 v[86:87], v[124:125], v[120:121], v[118:119]
	v_pk_add_f32 v[100:101], v[122:123], 1.0 op_sel_hi:[1,0]
	v_pk_fma_f32 v[98:99], v[116:117], v[88:89], v[98:99]
	v_rcp_f32_e32 v118, v100
	v_rcp_f32_e32 v119, v101
	v_mov_b32_dpp v100, v96 row_shr:1 row_mask:0xf bank_mask:0xf bound_ctrl:1
	v_mov_b32_dpp v101, v97 row_shr:1 row_mask:0xf bank_mask:0xf bound_ctrl:1
	v_pk_mul_f32 v[56:57], v[56:57], v[118:119]
	v_pk_fma_f32 v[96:97], v[128:129], v[120:121], v[110:111]
	v_pk_mul_f32 v[56:57], v[106:107], v[56:57]
	v_pk_fma_f32 v[96:97], v[124:125], v[100:101], v[96:97]
	v_pk_fma_f32 v[98:99], v[112:113], v[176:177], v[98:99]
	v_mov_b32_dpp v100, v88 row_shr:1 row_mask:0xf bank_mask:0xf bound_ctrl:1
	v_pk_mul_f32 v[106:107], v[96:97], s[82:83] op_sel_hi:[1,0]
	v_mov_b32_dpp v101, v89 row_shr:1 row_mask:0xf bank_mask:0xf bound_ctrl:1
	v_mov_b32_dpp v88, v92 row_shr:1 row_mask:0xf bank_mask:0xf bound_ctrl:1
	v_pk_mul_f32 v[110:111], v[46:47], s[82:83] op_sel_hi:[1,0]
	v_exp_f32_e32 v118, v106
	v_exp_f32_e32 v119, v107
	v_mov_b32_dpp v89, v93 row_shr:1 row_mask:0xf bank_mask:0xf bound_ctrl:1
	v_exp_f32_e32 v92, v110
	v_exp_f32_e32 v93, v111
	v_pk_fma_f32 v[106:107], v[116:117], v[88:89], v[114:115]
	v_pk_fma_f32 v[88:89], v[112:113], v[88:89], v[94:95]
	v_pk_mul_f32 v[94:95], v[90:91], s[82:83] op_sel_hi:[1,0]
	v_pk_fma_f32 v[100:101], v[112:113], v[100:101], v[106:107]
	v_pk_add_f32 v[92:93], v[92:93], 1.0 op_sel_hi:[1,0]
	v_exp_f32_e32 v106, v94
	v_exp_f32_e32 v107, v95
	v_rcp_f32_e32 v94, v92
	v_rcp_f32_e32 v95, v93
	v_pk_mul_f32 v[92:93], v[86:87], s[82:83] op_sel_hi:[1,0]
	v_pk_add_f32 v[106:107], v[106:107], 1.0 op_sel_hi:[1,0]
	v_pk_fma_f32 v[110:111], v[36:37], v[28:29], v[32:33]
	v_pk_mul_f32 v[46:47], v[46:47], v[94:95]
	v_exp_f32_e32 v94, v92
	v_exp_f32_e32 v95, v93
	v_pk_add_f32 v[92:93], v[118:119], 1.0 op_sel_hi:[1,0]
	v_mov_b32_dpp v112, v38 row_shr:1 row_mask:0xf bank_mask:0xf bound_ctrl:1
	v_mov_b32_dpp v113, v39 row_shr:1 row_mask:0xf bank_mask:0xf bound_ctrl:1
	v_pk_fma_f32 v[110:111], v[40:41], v[8:9], v[110:111]
	v_pk_add_f32 v[94:95], v[94:95], 1.0 op_sel_hi:[1,0]
	v_rcp_f32_e32 v114, v92
	v_rcp_f32_e32 v115, v93
	v_rcp_f32_e32 v92, v94
	v_rcp_f32_e32 v93, v95
	v_pk_mul_f32 v[94:95], v[96:97], v[114:115]
	v_pk_mul_f32 v[86:87], v[86:87], v[92:93]
	v_pk_mul_f32 v[92:93], v[100:101], v[94:95]
	v_rcp_f32_e32 v94, v106
	v_rcp_f32_e32 v95, v107
	v_mov_b32_dpp v96, v36 row_shr:1 row_mask:0xf bank_mask:0xf bound_ctrl:1
	v_mov_b32_dpp v97, v37 row_shr:1 row_mask:0xf bank_mask:0xf bound_ctrl:1
	v_mov_b32_e32 v0, v82
	v_mov_b32_dpp v36, v34 row_shr:1 row_mask:0xf bank_mask:0xf bound_ctrl:1
	v_mov_b32_dpp v37, v35 row_shr:1 row_mask:0xf bank_mask:0xf bound_ctrl:1
	v_pk_mul_f32 v[90:91], v[90:91], v[94:95]
	v_pk_fma_f32 v[34:35], v[34:35], v[26:27], v[30:31]
	v_mov_b32_dpp v94, v58 row_shr:1 row_mask:0xf bank_mask:0xf bound_ctrl:1
	v_mov_b32_dpp v100, v42 row_shr:1 row_mask:0xf bank_mask:0xf bound_ctrl:1
	v_mov_b32_dpp v101, v43 row_shr:1 row_mask:0xf bank_mask:0xf bound_ctrl:1
	v_pk_fma_f32 v[34:35], v[38:39], v[6:7], v[34:35]
	v_pk_fma_f32 v[42:43], v[42:43], v[18:19], v[22:23]
	v_mov_b32_dpp v95, v59 row_shr:1 row_mask:0xf bank_mask:0xf bound_ctrl:1
	v_pk_fma_f32 v[34:35], v[74:75], v[2:3], v[34:35]
	v_pk_fma_f32 v[42:43], v[58:59], v[14:15], v[42:43]
	v_pk_fma_f32 v[38:39], v[38:39], v[26:27], v[30:31]
	v_pk_fma_f32 v[106:107], v[74:75], v[26:27], v[30:31]
	v_pk_fma_f32 v[42:43], v[50:51], v[10:11], v[42:43]
	v_pk_fma_f32 v[38:39], v[74:75], v[6:7], v[38:39]
	v_pk_fma_f32 v[26:27], v[62:63], v[26:27], v[30:31]
	v_pk_mul_f32 v[30:31], v[42:43], s[82:83] op_sel_hi:[1,0]
	v_pk_fma_f32 v[38:39], v[62:63], v[2:3], v[38:39]
	v_pk_fma_f32 v[62:63], v[62:63], v[6:7], v[106:107]
	v_exp_f32_e32 v74, v30
	v_exp_f32_e32 v75, v31
	v_pk_fma_f32 v[6:7], v[6:7], v[36:37], v[26:27]
	v_pk_fma_f32 v[26:27], v[2:3], v[36:37], v[62:63]
	v_pk_fma_f32 v[30:31], v[58:59], v[18:19], v[22:23]
	v_pk_add_f32 v[36:37], v[74:75], 1.0 op_sel_hi:[1,0]
	v_pk_fma_f32 v[2:3], v[2:3], v[112:113], v[6:7]
	v_pk_fma_f32 v[6:7], v[76:77], v[4:5], v[110:111]
	v_rcp_f32_e32 v58, v36
	v_rcp_f32_e32 v59, v37
	v_pk_fma_f32 v[30:31], v[50:51], v[14:15], v[30:31]
	v_pk_fma_f32 v[36:37], v[40:41], v[28:29], v[32:33]
	v_pk_fma_f32 v[62:63], v[76:77], v[28:29], v[32:33]
	v_pk_mul_f32 v[42:43], v[42:43], v[58:59]
	v_pk_fma_f32 v[30:31], v[70:71], v[10:11], v[30:31]
	v_pk_fma_f32 v[36:37], v[76:77], v[8:9], v[36:37]
	v_pk_mul_f32 v[34:35], v[34:35], v[42:43]
	v_pk_mul_f32 v[42:43], v[30:31], s[82:83] op_sel_hi:[1,0]
	v_pk_fma_f32 v[36:37], v[64:65], v[4:5], v[36:37]
	v_mov_b32_dpp v58, v40 row_shr:1 row_mask:0xf bank_mask:0xf bound_ctrl:1
	v_exp_f32_e32 v74, v42
	v_exp_f32_e32 v75, v43
	v_pk_fma_f32 v[42:43], v[50:51], v[18:19], v[22:23]
	v_pk_fma_f32 v[18:19], v[70:71], v[18:19], v[22:23]
	v_pk_fma_f32 v[22:23], v[64:65], v[28:29], v[32:33]
	v_pk_add_f32 v[28:29], v[74:75], 1.0 op_sel_hi:[1,0]
	v_pk_fma_f32 v[32:33], v[70:71], v[14:15], v[42:43]
	v_pk_fma_f32 v[14:15], v[14:15], v[100:101], v[18:19]
	v_rcp_f32_e32 v18, v28
	v_rcp_f32_e32 v19, v29
	v_pk_fma_f32 v[28:29], v[10:11], v[100:101], v[32:33]
	v_pk_fma_f32 v[10:11], v[10:11], v[94:95], v[14:15]
	v_pk_mul_f32 v[14:15], v[30:31], v[18:19]
	v_pk_mul_f32 v[18:19], v[10:11], s[82:83] op_sel_hi:[1,0]
	v_pk_mul_f32 v[30:31], v[28:29], s[82:83] op_sel_hi:[1,0]
	v_pk_mul_f32 v[14:15], v[38:39], v[14:15]
	v_exp_f32_e32 v32, v18
	v_exp_f32_e32 v33, v19
	v_exp_f32_e32 v18, v30
	v_exp_f32_e32 v19, v31
	v_pk_fma_f32 v[30:31], v[64:65], v[8:9], v[62:63]
	v_pk_add_f32 v[32:33], v[32:33], 1.0 op_sel_hi:[1,0]
	v_mov_b32_dpp v59, v41 row_shr:1 row_mask:0xf bank_mask:0xf bound_ctrl:1
	v_pk_add_f32 v[18:19], v[18:19], 1.0 op_sel_hi:[1,0]
	v_rcp_f32_e32 v38, v32
	v_rcp_f32_e32 v39, v33
	v_rcp_f32_e32 v32, v18
	v_rcp_f32_e32 v33, v19
	v_pk_fma_f32 v[8:9], v[8:9], v[96:97], v[22:23]
	v_pk_mul_f32 v[10:11], v[10:11], v[38:39]
	v_pk_fma_f32 v[18:19], v[4:5], v[96:97], v[30:31]
	v_pk_mul_f32 v[22:23], v[28:29], v[32:33]
	v_pk_mul_f32 v[2:3], v[2:3], v[10:11]
	v_pk_fma_f32 v[4:5], v[4:5], v[58:59], v[8:9]
	v_pk_mul_f32 v[8:9], v[26:27], v[22:23]
	v_mov_b32_e32 v49, v78
	v_mov_b32_e32 v57, v57
	v_mov_b32_dpp v10, v44 row_shr:1 row_mask:0xf bank_mask:0xf bound_ctrl:1
	v_mov_b32_dpp v11, v45 row_shr:1 row_mask:0xf bank_mask:0xf bound_ctrl:1
	v_mov_b32_dpp v22, v60 row_shr:1 row_mask:0xf bank_mask:0xf bound_ctrl:1
	v_mov_b32_dpp v23, v61 row_shr:1 row_mask:0xf bank_mask:0xf bound_ctrl:1
	v_pk_fma_f32 v[26:27], v[44:45], v[20:21], v[24:25]
	v_pk_fma_f32 v[28:29], v[60:61], v[20:21], v[24:25]
	v_pk_mul_f32 v[30:31], v[98:99], v[46:47]
	v_pk_fma_f32 v[26:27], v[60:61], v[16:17], v[26:27]
	v_pk_fma_f32 v[28:29], v[52:53], v[16:17], v[28:29]
	v_pk_mul_f32 v[32:33], v[102:103], v[90:91]
	v_pk_fma_f32 v[26:27], v[52:53], v[12:13], v[26:27]
	v_pk_fma_f32 v[28:29], v[72:73], v[12:13], v[28:29]
	v_pk_mul_f32 v[38:39], v[88:89], v[86:87]
	v_pk_mul_f32 v[40:41], v[26:27], s[82:83] op_sel_hi:[1,0]
	v_pk_mul_f32 v[42:43], v[28:29], s[82:83] op_sel_hi:[1,0]
	v_mov_b32_e32 v8, v8
	v_exp_f32_e32 v44, v40
	v_exp_f32_e32 v45, v41
	v_exp_f32_e32 v40, v42
	v_exp_f32_e32 v41, v43
	v_pk_fma_f32 v[42:43], v[52:53], v[20:21], v[24:25]
	v_pk_add_f32 v[44:45], v[44:45], 1.0 op_sel_hi:[1,0]
	v_pk_fma_f32 v[20:21], v[72:73], v[20:21], v[24:25]
	v_pk_add_f32 v[24:25], v[40:41], 1.0 op_sel_hi:[1,0]
	v_rcp_f32_e32 v40, v44
	v_rcp_f32_e32 v41, v45
	v_rcp_f32_e32 v44, v24
	v_rcp_f32_e32 v45, v25
	v_pk_fma_f32 v[24:25], v[72:73], v[16:17], v[42:43]
	v_pk_mul_f32 v[26:27], v[26:27], v[40:41]
	v_pk_fma_f32 v[16:17], v[16:17], v[10:11], v[20:21]
	v_pk_mul_f32 v[20:21], v[28:29], v[44:45]
	v_pk_mul_f32 v[6:7], v[6:7], v[26:27]
	v_pk_fma_f32 v[10:11], v[12:13], v[10:11], v[24:25]
	v_pk_fma_f32 v[12:13], v[12:13], v[22:23], v[16:17]
	v_pk_mul_f32 v[16:17], v[36:37], v[20:21]
	v_pk_mul_f32 v[20:21], v[10:11], s[82:83] op_sel_hi:[1,0]
	v_pk_mul_f32 v[22:23], v[12:13], s[82:83] op_sel_hi:[1,0]
	v_mov_b32_e32 v6, v6
	v_exp_f32_e32 v24, v20
	v_exp_f32_e32 v26, v22
	v_exp_f32_e32 v27, v23
	v_exp_f32_e32 v25, v21
	v_mov_b32_e32 v17, v17
	v_pk_add_f32 v[20:21], v[26:27], 1.0 op_sel_hi:[1,0]
	v_pk_add_f32 v[22:23], v[24:25], 1.0 op_sel_hi:[1,0]
	v_rcp_f32_e32 v24, v20
	v_rcp_f32_e32 v25, v21
	v_rcp_f32_e32 v20, v22
	v_rcp_f32_e32 v21, v23
	v_pk_mul_f32 v[12:13], v[12:13], v[24:25]
	v_pk_mul_f32 v[10:11], v[10:11], v[20:21]
	v_pk_mul_f32 v[4:5], v[4:5], v[12:13]
	v_pk_mul_f32 v[10:11], v[18:19], v[10:11]
	v_mov_b32_e32 v4, v4
	v_add_u32_e32 v78, 0x80, v48
	v_cvt_pk_bf16_f32 v22, v2, v3
	v_mov_b64_e32 v[2:3], s[12:13]
	v_add_u32_e32 v82, 0x81, v48
	v_cvt_pk_bf16_f32 v20, v56, v57
	v_mad_i64_i32 v[12:13], s[2:3], v78, s94, v[2:3]
	v_mad_i64_i32 v[2:3], s[2:3], v82, s94, v[2:3]
	v_cvt_pk_bf16_f32 v21, v92, v93
	v_cvt_pk_bf16_f32 v23, v4, v5
	v_lshl_add_u64 v[4:5], v[12:13], 0, v[54:55]
	v_cvt_pk_bf16_f32 v24, v49, v79
	v_cvt_pk_bf16_f32 v25, v38, v39
	v_cvt_pk_bf16_f32 v26, v8, v9
	v_cvt_pk_bf16_f32 v27, v10, v11
	v_lshl_add_u64 v[2:3], v[2:3], 0, v[54:55]
	s_mov_b64 exec, s[98:99]
	global_store_dwordx4 v[4:5], v[20:23], off
	s_mov_b64 exec, -1
	v_add_u32_e32 v49, 0x82, v48
	s_mov_b64 exec, s[98:99]
	global_store_dwordx4 v[2:3], v[24:27], off
	s_mov_b64 exec, -1
	v_mov_b64_e32 v[8:9], s[12:13]
	v_add_u32_e32 v48, 0x83, v48
	v_cvt_pk_bf16_f32 v20, v0, v83
	v_mad_i64_i32 v[2:3], s[0:1], v49, s94, v[8:9]
	v_cvt_pk_bf16_f32 v21, v32, v33
	v_cvt_pk_bf16_f32 v22, v14, v15
	v_cvt_pk_bf16_f32 v23, v16, v17
	v_lshl_add_u64 v[2:3], v[2:3], 0, v[54:55]
	v_mad_i64_i32 v[4:5], s[0:1], v48, s94, v[8:9]
	v_cvt_pk_bf16_f32 v8, v66, v67
	global_store_dwordx4 v[2:3], v[20:23], off
	v_cvt_pk_bf16_f32 v9, v30, v31
	v_cvt_pk_bf16_f32 v10, v34, v35
	v_cvt_pk_bf16_f32 v11, v6, v7
	v_lshl_add_u64 v[2:3], v[4:5], 0, v[54:55]
	global_store_dwordx4 v[2:3], v[8:11], off
	s_andn2_b64 vcc, exec, s[4:5]
	s_mov_b64 s[0:1], -1
	s_cbranch_vccnz .LBB0_694
	s_andn2_b64 vcc, exec, s[8:9]
	s_cbranch_vccnz .LBB0_693
	s_barrier
	s_branch .LBB0_693

	.amdhsa_kernel _Z6mk_fwd4Args
		.amdhsa_group_segment_fixed_size 0
		.amdhsa_private_segment_fixed_size 0
		.amdhsa_kernarg_size 432
		.amdhsa_user_sgpr_count 2
		.amdhsa_user_sgpr_dispatch_ptr 0
		.amdhsa_user_sgpr_queue_ptr 0
		.amdhsa_user_sgpr_kernarg_segment_ptr 1
		.amdhsa_user_sgpr_dispatch_id 0
		.amdhsa_user_sgpr_kernarg_preload_length 0
		.amdhsa_user_sgpr_kernarg_preload_offset 0
		.amdhsa_user_sgpr_private_segment_size 0
		.amdhsa_uses_dynamic_stack 0
		.amdhsa_enable_private_segment 0
		.amdhsa_system_sgpr_workgroup_id_x 1
		.amdhsa_system_sgpr_workgroup_id_y 0
		.amdhsa_system_sgpr_workgroup_id_z 0
		.amdhsa_system_sgpr_workgroup_info 0
		.amdhsa_system_vgpr_workitem_id 2
		.amdhsa_next_free_vgpr 256
		.amdhsa_next_free_sgpr 100
		.amdhsa_accum_offset 256
		.amdhsa_reserve_vcc 1
		.amdhsa_float_round_mode_32 0
		.amdhsa_float_round_mode_16_64 0
		.amdhsa_float_denorm_mode_32 3
		.amdhsa_float_denorm_mode_16_64 3
		.amdhsa_dx10_clamp 1
		.amdhsa_ieee_mode 1
		.amdhsa_fp16_overflow 0
		.amdhsa_tg_split 0
		.amdhsa_exception_fp_ieee_invalid_op 0
		.amdhsa_exception_fp_denorm_src 0
		.amdhsa_exception_fp_ieee_div_zero 0
		.amdhsa_exception_fp_ieee_overflow 0
		.amdhsa_exception_fp_ieee_underflow 0
		.amdhsa_exception_fp_ieee_inexact 0
		.amdhsa_exception_int_div_zero 0
	.end_amdhsa_kernel

amdhsa.kernels:
  - .agpr_count:     0
    .args:
      - .offset:         0
        .size:           176
        .value_kind:     by_value
      - .offset:         176
        .size:           4
        .value_kind:     hidden_block_count_x
      - .offset:         180
        .size:           4
        .value_kind:     hidden_block_count_y
      - .offset:         184
        .size:           4
        .value_kind:     hidden_block_count_z
      - .offset:         188
        .size:           2
        .value_kind:     hidden_group_size_x
      - .offset:         190
        .size:           2
        .value_kind:     hidden_group_size_y
      - .offset:         192
        .size:           2
        .value_kind:     hidden_group_size_z
      - .offset:         194
        .size:           2
        .value_kind:     hidden_remainder_x
      - .offset:         196
        .size:           2
        .value_kind:     hidden_remainder_y
      - .offset:         198
        .size:           2
        .value_kind:     hidden_remainder_z
      - .offset:         216
        .size:           8
        .value_kind:     hidden_global_offset_x
      - .offset:         224
        .size:           8
        .value_kind:     hidden_global_offset_y
      - .offset:         232
        .size:           8
        .value_kind:     hidden_global_offset_z
      - .offset:         240
        .size:           2
        .value_kind:     hidden_grid_dims
      - .offset:         264
        .size:           8
        .value_kind:     hidden_multigrid_sync_arg
      - .offset:         296
        .size:           4
        .value_kind:     hidden_dynamic_lds_size
    .group_segment_fixed_size: 0
    .kernarg_segment_align: 8
    .kernarg_segment_size: 432
    .language:       OpenCL C
    .language_version:
      - 2
      - 0
    .max_flat_workgroup_size: 512
    .name:           _Z6mk_fwd4Args
    .private_segment_fixed_size: 0
    .sgpr_count:     106
    .sgpr_spill_count: 36
    .symbol:         _Z6mk_fwd4Args.kd
    .uniform_work_group_size: 1
    .uses_dynamic_stack: false
    .vgpr_count:     256
    .vgpr_spill_count: 0
    .wavefront_size: 64
